# P0 w_qb/w_kvb transposes: 64 serial load-drain round trips per item replaced by 16 loads per iteration with one wait (stacked on FFT load de-serialization, P8, attention)
# speedup vs baseline: 1.0150x; 1.0150x over previous
.LBB0_38:
	s_and_b64 vcc, exec, s[36:37]
	s_cbranch_vccz .Lp0_kvb_slow
.Lp0_kvb_fast:
	v_lshl_add_u64 v[24:25], v[18:19], 0, s[26:27]
	global_load_dword v100, v[24:25], off
	v_lshl_add_u64 v[24:25], v[16:17], 0, s[26:27]
	global_load_dword v101, v[24:25], off
	v_lshl_add_u64 v[24:25], v[14:15], 0, s[26:27]
	global_load_dword v102, v[24:25], off
	v_lshl_add_u64 v[24:25], v[12:13], 0, s[26:27]
	global_load_dword v103, v[24:25], off
	v_lshl_add_u64 v[24:25], v[10:11], 0, s[26:27]
	global_load_dword v104, v[24:25], off
	v_lshl_add_u64 v[24:25], v[8:9], 0, s[26:27]
	global_load_dword v105, v[24:25], off
	v_lshl_add_u64 v[24:25], v[6:7], 0, s[26:27]
	global_load_dword v106, v[24:25], off
	v_lshl_add_u64 v[24:25], v[4:5], 0, s[26:27]
	global_load_dword v107, v[24:25], off
	v_lshl_add_u64 v[24:25], s[8:9], 0, v[34:35]
	global_load_dword v108, v[24:25], off
	v_lshl_add_u64 v[20:21], s[8:9], 0, v[2:3]
	global_load_dword v109, v[20:21], off offset:8
	global_load_dword v110, v[20:21], off offset:16
	global_load_dword v111, v[20:21], off offset:24
	global_load_dword v112, v[20:21], off offset:32
	global_load_dword v113, v[20:21], off offset:40
	global_load_dword v114, v[20:21], off offset:48
	global_load_dword v115, v[20:21], off offset:56
	s_waitcnt vmcnt(0)
	v_mul_f32_e32 v100, 0x41800000, v100
	v_mul_f32_e32 v100, v100, v108
	ds_write_b32 v22, v100
	v_mul_f32_e32 v101, 0x41800000, v101
	v_mul_f32_e32 v101, v101, v109
	ds_write_b32 v22, v101 offset:264
	v_mul_f32_e32 v102, 0x41800000, v102
	v_mul_f32_e32 v102, v102, v110
	ds_write_b32 v22, v102 offset:528
	v_mul_f32_e32 v103, 0x41800000, v103
	v_mul_f32_e32 v103, v103, v111
	ds_write_b32 v22, v103 offset:792
	v_mul_f32_e32 v104, 0x41800000, v104
	v_mul_f32_e32 v104, v104, v112
	ds_write_b32 v22, v104 offset:1056
	v_mul_f32_e32 v105, 0x41800000, v105
	v_mul_f32_e32 v105, v105, v113
	ds_write_b32 v22, v105 offset:1320
	v_mul_f32_e32 v106, 0x41800000, v106
	v_mul_f32_e32 v106, v106, v114
	ds_write_b32 v22, v106 offset:1584
	v_mul_f32_e32 v107, 0x41800000, v107
	v_mul_f32_e32 v107, v107, v115
	ds_write_b32 v22, v107 offset:1848
	s_add_u32 s26, s26, 0x40000
	s_addc_u32 s27, s27, 0
	s_add_u32 s8, s8, 64
	s_addc_u32 s9, s9, 0
	s_cmp_lg_u32 s26, 0x100000
	v_add_u32_e32 v22, 0x840, v22
	s_cbranch_scc1 .Lp0_kvb_fast
	s_branch .LBB0_54

.Lp0_qb_fast:
	v_lshl_add_u64 v[24:25], v[18:19], 0, s[26:27]
	global_load_dword v100, v[24:25], off
	v_lshl_add_u64 v[24:25], v[16:17], 0, s[26:27]
	global_load_dword v101, v[24:25], off
	v_lshl_add_u64 v[24:25], v[14:15], 0, s[26:27]
	global_load_dword v102, v[24:25], off
	v_lshl_add_u64 v[24:25], v[12:13], 0, s[26:27]
	global_load_dword v103, v[24:25], off
	v_lshl_add_u64 v[24:25], v[10:11], 0, s[26:27]
	global_load_dword v104, v[24:25], off
	v_lshl_add_u64 v[24:25], v[8:9], 0, s[26:27]
	global_load_dword v105, v[24:25], off
	v_lshl_add_u64 v[24:25], v[6:7], 0, s[26:27]
	global_load_dword v106, v[24:25], off
	v_lshl_add_u64 v[24:25], v[2:3], 0, s[26:27]
	global_load_dword v107, v[24:25], off
	v_lshl_add_u64 v[24:25], s[8:9], 0, v[34:35]
	global_load_dword v108, v[24:25], off
	v_lshl_add_u64 v[20:21], s[8:9], 0, v[4:5]
	global_load_dword v109, v[20:21], off offset:8
	global_load_dword v110, v[20:21], off offset:16
	global_load_dword v111, v[20:21], off offset:24
	global_load_dword v112, v[20:21], off offset:32
	global_load_dword v113, v[20:21], off offset:40
	global_load_dword v114, v[20:21], off offset:48
	global_load_dword v115, v[20:21], off offset:56
	s_waitcnt vmcnt(0)
	v_mul_f32_e32 v100, 0x42000000, v100
	v_mul_f32_e32 v100, v100, v108
	ds_write_b32 v22, v100
	v_mul_f32_e32 v101, 0x42000000, v101
	v_mul_f32_e32 v101, v101, v109
	ds_write_b32 v22, v101 offset:264
	v_mul_f32_e32 v102, 0x42000000, v102
	v_mul_f32_e32 v102, v102, v110
	ds_write_b32 v22, v102 offset:528
	v_mul_f32_e32 v103, 0x42000000, v103
	v_mul_f32_e32 v103, v103, v111
	ds_write_b32 v22, v103 offset:792
	v_mul_f32_e32 v104, 0x42000000, v104
	v_mul_f32_e32 v104, v104, v112
	ds_write_b32 v22, v104 offset:1056
	v_mul_f32_e32 v105, 0x42000000, v105
	v_mul_f32_e32 v105, v105, v113
	ds_write_b32 v22, v105 offset:1320
	v_mul_f32_e32 v106, 0x42000000, v106
	v_mul_f32_e32 v106, v106, v114
	ds_write_b32 v22, v106 offset:1584
	v_mul_f32_e32 v107, 0x42000000, v107
	v_mul_f32_e32 v107, v107, v115
	ds_write_b32 v22, v107 offset:1848
	s_add_u32 s26, s26, 0x30000
	s_addc_u32 s27, s27, 0
	s_add_u32 s8, s8, 64
	s_addc_u32 s9, s9, 0
	s_cmp_lg_u32 s26, 0xc0000
	v_add_u32_e32 v22, 0x840, v22
	s_cbranch_scc1 .Lp0_qb_fast
	s_branch .LBB0_75
